# v13
# speedup vs baseline: 1.0509x; 1.0007x over previous
; #define SBAR() __builtin_amdgcn_sched_barrier(0)
; #define SLOAD(i, k0) do { sr_[i].vs0 = *reinterpret_cast<const bf16x8*>(&Vh[(size_t)((k0) + sr) * ldk + sc]); sr_[i].vs1 = *reinterpret_cast<const bf16x8*>(&Vh[(size_t)((k0) + 32 + sr) * ldk + sc]); \
;     sr_[i].ks0 = *reinterpret_cast<const bf16x8*>(&Kh[(size_t)((k0) + sr) * ldk + sc]); sr_[i].ks1 = *reinterpret_cast<const bf16x8*>(&Kh[(size_t)((k0) + 32 + sr) * ldk + sc]); } while (0)
; #define SWRITE(b, i) do { *(bf16x8*)((char*)V_lds + (b) * SHM_V + vst0) = sr_[i].vs0;          \
;     *(bf16x8*)((char*)V_lds + (b) * SHM_V + vst1) = sr_[i].vs1; int kc = sc * 2;               \
;     *(bf16x8*)((char*)K_lds + (b) * SHM_K + KSWZ(sr, kc)) = sr_[i].ks0;                       \
;     *(bf16x8*)((char*)K_lds + (b) * SHM_K + KSWZ(32 + sr, kc)) = sr_[i].ks1; } while (0)
; #define SWAIT() asm volatile("s_waitcnt vmcnt(4)" ::: "memory")
; template <int ND0>
; DEVINL void qkt(f32x16& p0, f32x16& p1, const bf16* Ks, const bf16x8* qr, int r32, int hi, int colbase) {
;   p0 = f32x16{}; p1 = f32x16{};
;   __builtin_amdgcn_iglp_opt(1);
; #pragma unroll
;   for (int d0 = 0; d0 < ND0; ++d0) { int cb = (colbase + d0 * 16 + hi * 8) * 2;
;     bf16x8 b0 = *reinterpret_cast<const bf16x8*>((const char*)Ks + KSWZ(r32, cb));
;     bf16x8 b1 = *reinterpret_cast<const bf16x8*>((const char*)Ks + KSWZ(32 + r32, cb));
;     p0 = __builtin_amdgcn_mfma_f32_32x32x16_bf16(b0, qr[d0], p0, 0, 0, 0);
;     p1 = __builtin_amdgcn_mfma_f32_32x32x16_bf16(b1, qr[d0], p1, 0, 0, 0); }
; }
; template <bool DIFF, bool FAST> ...
;     ...
;   for (int j = 1; j + 1 < NT; j += 2) {
;     SBAR(); qkt<ND0>(pB0, pB1, (bf16*)((char*)K_lds + SHM_K), qr, r32, hi, colbase);
;     finishSM_bal(pA1, psA, l_reg, pa2, pa3); SBAR();
;     SLOAD(SO, (j + 2) * KVBLK); SBAR();
;     pv_d0(o, vb0, paA0, paA1, pa2, pa3); partialSM_bal(pB0, psB, paB0, paB1);
;     __syncthreads(); SWAIT(); SWRITE(0, SE);
.LBB0_564:
	v_readfirstlane_b32 vcc_lo, v217
	s_lshr_b32 vcc_lo, vcc_lo, 6
	s_lshl_b32 vcc_lo, vcc_lo, 10
	s_mov_b32 vcc_hi, 0x10000
	v_lshrrev_b32_e32 v233, 4, v217
	v_and_b32_e32 v220, 15, v233
	v_xor_b32_e32 v220, v220, v217
	v_and_b32_e32 v220, 15, v220
	v_lshlrev_b32_e32 v233, 9, v233
	v_lshl_add_u32 v233, v220, 4, v233
	v_bfe_u32 v218, v217, 2, 2
	v_bfe_u32 v220, v217, 7, 1
	v_lshl_or_b32 v218, v220, 2, v218
	v_bfe_u32 v220, v217, 4, 1
	v_lshl_or_b32 v218, v220, 3, v218
	v_bfe_u32 v220, v217, 8, 1
	v_lshl_or_b32 v218, v220, 4, v218
	v_lshlrev_b32_e32 v218, 9, v218
	v_and_b32_e32 v220, 3, v217
	v_lshl_or_b32 v218, v220, 4, v218
	v_bfe_u32 v220, v217, 5, 2
	v_lshl_or_b32 v218, v220, 6, v218
	s_waitcnt vmcnt(0)
	ds_read_b128 v[170:173], v224 offset:49152
	ds_read_b128 v[174:177], v224 offset:57344
	ds_read_b128 v[178:181], v225 offset:49152
	ds_read_b128 v[182:185], v225 offset:57344
.Lattn_gqa_top:
	ds_read_b128 v[234:237], v226 offset:49152
	ds_read_b128 v[238:241], v226 offset:57344
	ds_read_b128 v[242:245], v227 offset:49152
	s_add_i32 s9, s7, -2
	s_lshl_b32 s9, s9, 15
	s_add_u32 s26, s10, s9
	s_addc_u32 s27, s11, 0
	s_add_u32 m0, vcc_lo, vcc_hi
	s_nop 0
	global_load_lds_dwordx4 v218, s[26:27]
	v_exp_f32_e32 v64, v64
	v_exp_f32_e32 v65, v65
	s_waitcnt lgkmcnt(6)
	v_mfma_f32_32x32x16_bf16 v[96:111], v[170:173], v[142:145], 0
	ds_read_b128 v[170:173], v227 offset:57344
	s_add_u32 s26, s26, 0x4000
	s_addc_u32 s27, s27, 0
	s_add_u32 m0, m0, 0x2000
	s_nop 0
	global_load_lds_dwordx4 v218, s[26:27]
	v_exp_f32_e32 v66, v66
	v_exp_f32_e32 v67, v67
	s_waitcnt lgkmcnt(6)
	v_mfma_f32_32x32x16_bf16 v[80:95], v[174:177], v[142:145], 0
	ds_read_b128 v[174:177], v228 offset:49152
	s_add_u32 s26, s28, s9
	s_addc_u32 s27, s29, 0
	s_add_u32 m0, vcc_lo, 0x8000
	s_nop 0
	global_load_lds_dwordx4 v233, s[26:27]
	v_exp_f32_e32 v68, v68
	v_exp_f32_e32 v69, v69
	s_waitcnt lgkmcnt(6)
	v_mfma_f32_32x32x16_bf16 v[96:111], v[178:181], v[138:141], v[96:111]
	ds_read_b128 v[178:181], v228 offset:57344
	s_add_u32 s26, s26, 0x4000
	s_addc_u32 s27, s27, 0
	s_add_u32 m0, m0, 0x2000
	s_nop 0
	global_load_lds_dwordx4 v233, s[26:27]
	v_exp_f32_e32 v70, v70
	v_exp_f32_e32 v71, v71
	s_waitcnt lgkmcnt(6)
	v_mfma_f32_32x32x16_bf16 v[80:95], v[182:185], v[138:141], v[80:95]
	v_exp_f32_e32 v72, v72
	v_exp_f32_e32 v73, v73
	s_waitcnt lgkmcnt(5)
	v_mfma_f32_32x32x16_bf16 v[96:111], v[234:237], v[134:137], v[96:111]
	ds_read_b128 v[234:237], v229 offset:49152
	v_exp_f32_e32 v74, v74
	v_exp_f32_e32 v75, v75
	s_waitcnt lgkmcnt(5)
	v_mfma_f32_32x32x16_bf16 v[80:95], v[238:241], v[134:137], v[80:95]
	ds_read_b128 v[238:241], v229 offset:57344
	v_exp_f32_e32 v76, v76
	v_exp_f32_e32 v77, v77
	s_waitcnt lgkmcnt(5)
	v_mfma_f32_32x32x16_bf16 v[96:111], v[242:245], v[130:133], v[96:111]
	ds_read_b128 v[242:245], v231 offset:49152
	v_exp_f32_e32 v78, v78
	v_exp_f32_e32 v79, v79
	s_waitcnt lgkmcnt(5)
	v_mfma_f32_32x32x16_bf16 v[80:95], v[170:173], v[130:133], v[80:95]
	ds_read_b128 v[170:173], v231 offset:57344
	v_add_f32_e32 v197, v194, v64
	v_add_f32_e32 v197, v65, v197
	v_add_f32_e32 v197, v66, v197
	v_add_f32_e32 v197, v67, v197
	s_waitcnt lgkmcnt(5)
	v_mfma_f32_32x32x16_bf16 v[96:111], v[174:177], v[126:129], v[96:111]
	ds_read_b128 v[174:177], v230 offset:49152
	v_add_f32_e32 v197, v68, v197
	v_add_f32_e32 v197, v69, v197
	v_add_f32_e32 v197, v70, v197
	v_add_f32_e32 v197, v71, v197
	s_waitcnt lgkmcnt(5)
	v_mfma_f32_32x32x16_bf16 v[80:95], v[178:181], v[126:129], v[80:95]
	ds_read_b128 v[178:181], v230 offset:57344
	v_add_f32_e32 v197, v72, v197
	v_add_f32_e32 v197, v73, v197
	v_add_f32_e32 v197, v74, v197
	v_add_f32_e32 v197, v75, v197
	s_waitcnt lgkmcnt(5)
	v_mfma_f32_32x32x16_bf16 v[96:111], v[234:237], v[122:125], v[96:111]
	v_add_f32_e32 v197, v76, v197
	v_add_f32_e32 v197, v77, v197
	v_add_f32_e32 v197, v78, v197
	v_add_f32_e32 v197, v79, v197
	s_waitcnt lgkmcnt(4)
	v_mfma_f32_32x32x16_bf16 v[80:95], v[238:241], v[122:125], v[80:95]
	v_cvt_pk_bf16_f32 v64, v64, v65
	v_cvt_pk_bf16_f32 v65, v66, v67
	v_cvt_pk_bf16_f32 v66, v68, v69
	v_cvt_pk_bf16_f32 v67, v70, v71
	s_waitcnt lgkmcnt(3)
	v_mfma_f32_32x32x16_bf16 v[96:111], v[242:245], v[118:121], v[96:111]
	v_cvt_pk_bf16_f32 v68, v72, v73
	v_cvt_pk_bf16_f32 v69, v74, v75
	v_cvt_pk_bf16_f32 v70, v76, v77
	v_cvt_pk_bf16_f32 v71, v78, v79
	s_waitcnt lgkmcnt(2)
	v_mfma_f32_32x32x16_bf16 v[80:95], v[170:173], v[118:121], v[80:95]
	v_mov_b32_e32 v195, v197
	v_permlane32_swap_b32_e32 v64, v66
	v_permlane32_swap_b32_e32 v65, v67
	v_permlane32_swap_b32_e32 v68, v70
	s_waitcnt lgkmcnt(1)
	v_mfma_f32_32x32x16_bf16 v[96:111], v[174:177], v[114:117], v[96:111]
	v_permlane32_swap_b32_e32 v69, v71
	v_permlane32_swap_b32_e32 v197, v195
	s_waitcnt lgkmcnt(0)
	v_mfma_f32_32x32x16_bf16 v[80:95], v[178:181], v[114:117], v[80:95]
	ds_read_b64_tr_b16 v[72:73], v191 offset:0
	ds_read_b64_tr_b16 v[74:75], v191 offset:0x800
	ds_read_b64_tr_b16 v[76:77], v191 offset:0x1000
	ds_read_b64_tr_b16 v[78:79], v191 offset:0x1800
	ds_read_b64_tr_b16 v[234:235], v191 offset:0x2000
	ds_read_b64_tr_b16 v[236:237], v191 offset:0x2800
	ds_read_b64_tr_b16 v[238:239], v191 offset:0x3000
	ds_read_b64_tr_b16 v[240:241], v191 offset:0x3800
	s_waitcnt lgkmcnt(6)
	v_mfma_f32_32x32x16_bf16 v[48:63], v[146:149], v[72:75], v[48:63]
	ds_read_b64_tr_b16 v[72:73], v191 offset:0x200
	ds_read_b64_tr_b16 v[74:75], v191 offset:0xa00
	v_exp_f32_e32 v96, v96
	v_exp_f32_e32 v97, v97
	s_waitcnt lgkmcnt(6)
	v_mfma_f32_32x32x16_bf16 v[48:63], v[150:153], v[76:79], v[48:63]
	ds_read_b64_tr_b16 v[76:77], v191 offset:0x1200
	ds_read_b64_tr_b16 v[78:79], v191 offset:0x1a00
	v_exp_f32_e32 v98, v98
	v_exp_f32_e32 v99, v99
	s_waitcnt lgkmcnt(6)
; #define SBAR() __builtin_amdgcn_sched_barrier(0)
; #define SLOAD(i, k0) do { sr_[i].vs0 = *reinterpret_cast<const bf16x8*>(&Vh[(size_t)((k0) + sr) * ldk + sc]); sr_[i].vs1 = *reinterpret_cast<const bf16x8*>(&Vh[(size_t)((k0) + 32 + sr) * ldk + sc]); \
;     sr_[i].ks0 = *reinterpret_cast<const bf16x8*>(&Kh[(size_t)((k0) + sr) * ldk + sc]); sr_[i].ks1 = *reinterpret_cast<const bf16x8*>(&Kh[(size_t)((k0) + 32 + sr) * ldk + sc]); } while (0)
; #define SWAIT() asm volatile("s_waitcnt vmcnt(4)" ::: "memory")
; template <int OFF> DEVINL s16x4 tr_read(int vb) {
;   s16x4 r; asm volatile("ds_read_b64_tr_b16 %0, %1 offset:%2" : "=&v"(r) : "v"(vb), "i"(OFF) : "memory"); return r;
; }
; template <int D0> DEVINL void pv_one(f32x16& od, int vb, bf16x8 pa0, bf16x8 pa1, bf16x8 pa2, bf16x8 pa3) {
;   const s16x4 l0 = tr_read<v_rd_off(D0, 0, 0)>(vb), h0 = tr_read<v_rd_off(D0, 0, 1)>(vb), l1 = tr_read<v_rd_off(D0, 1, 0)>(vb), h1 = tr_read<v_rd_off(D0, 1, 1)>(vb);
;   const s16x4 l2 = tr_read<v_rd_off(D0, 2, 0)>(vb), h2 = tr_read<v_rd_off(D0, 2, 1)>(vb), l3 = tr_read<v_rd_off(D0, 3, 0)>(vb), h3 = tr_read<v_rd_off(D0, 3, 1)>(vb);
;   asm volatile("s_waitcnt lgkmcnt(0)" ::: "memory"); SBAR();
;     ...
;   od = __builtin_amdgcn_mfma_f32_32x32x16_bf16(pa0, PK(l0, h0), od, 0, 0, 0);
;   od = __builtin_amdgcn_mfma_f32_32x32x16_bf16(pa1, PK(l1, h1), od, 0, 0, 0);
;   od = __builtin_amdgcn_mfma_f32_32x32x16_bf16(pa2, PK(l2, h2), od, 0, 0, 0);
;   od = __builtin_amdgcn_mfma_f32_32x32x16_bf16(pa3, PK(l3, h3), od, 0, 0, 0);
;     ...
; }
; DEVINL void pv_d0(f32x16* o, int vb, bf16x8 pa0, bf16x8 pa1, bf16x8 pa2, bf16x8 pa3) {
;   pv_one<0>(o[0], vb, pa0, pa1, pa2, pa3); pv_one<1>(o[1], vb, pa0, pa1, pa2, pa3); pv_one<2>(o[2], vb, pa0, pa1, pa2, pa3); pv_one<3>(o[3], vb, pa0, pa1, pa2, pa3);
; }
; template <bool DIFF, bool FAST> ...
;     ...
;     SLOAD(SO, (j + 2) * KVBLK); SBAR();
;     pv_d0(o, vb0, paA0, paA1, pa2, pa3); partialSM_bal(pB0, psB, paB0, paB1);
;     __syncthreads(); SWAIT(); SWRITE(0, SE);
;     __syncthreads();
;     SBAR(); qkt<ND0>(pA0, pA1, K_lds, qr, r32, hi, colbase);
;     finishSM_bal(pB1, psB, l_reg, pa2, pa3); SBAR();
	v_mfma_f32_32x32x16_bf16 v[48:63], v[64:67], v[234:237], v[48:63]
	ds_read_b64_tr_b16 v[234:235], v191 offset:0x2200
	ds_read_b64_tr_b16 v[236:237], v191 offset:0x2a00
	v_exp_f32_e32 v100, v100
	v_exp_f32_e32 v101, v101
	s_waitcnt lgkmcnt(6)
	v_mfma_f32_32x32x16_bf16 v[48:63], v[68:71], v[238:241], v[48:63]
	ds_read_b64_tr_b16 v[238:239], v191 offset:0x3200
	ds_read_b64_tr_b16 v[240:241], v191 offset:0x3a00
	v_exp_f32_e32 v102, v102
	v_exp_f32_e32 v103, v103
	s_waitcnt lgkmcnt(6)
	v_mfma_f32_32x32x16_bf16 v[32:47], v[146:149], v[72:75], v[32:47]
	ds_read_b64_tr_b16 v[72:73], v191 offset:0x400
	ds_read_b64_tr_b16 v[74:75], v191 offset:0xc00
	v_exp_f32_e32 v104, v104
	v_exp_f32_e32 v105, v105
	s_waitcnt lgkmcnt(6)
	v_mfma_f32_32x32x16_bf16 v[32:47], v[150:153], v[76:79], v[32:47]
	ds_read_b64_tr_b16 v[76:77], v191 offset:0x1400
	ds_read_b64_tr_b16 v[78:79], v191 offset:0x1c00
	v_exp_f32_e32 v106, v106
	v_exp_f32_e32 v107, v107
	s_waitcnt lgkmcnt(6)
	v_mfma_f32_32x32x16_bf16 v[32:47], v[64:67], v[234:237], v[32:47]
	ds_read_b64_tr_b16 v[234:235], v191 offset:0x2400
	ds_read_b64_tr_b16 v[236:237], v191 offset:0x2c00
	v_exp_f32_e32 v108, v108
	v_exp_f32_e32 v109, v109
	v_add_f32_e32 v192, 0, v96
	v_add_f32_e32 v192, v97, v192
	s_waitcnt lgkmcnt(6)
	v_mfma_f32_32x32x16_bf16 v[32:47], v[68:71], v[238:241], v[32:47]
	ds_read_b64_tr_b16 v[238:239], v191 offset:0x3400
	ds_read_b64_tr_b16 v[240:241], v191 offset:0x3c00
	v_exp_f32_e32 v110, v110
	v_exp_f32_e32 v111, v111
	v_add_f32_e32 v192, v98, v192
	v_add_f32_e32 v192, v99, v192
	s_waitcnt lgkmcnt(6)
	v_mfma_f32_32x32x16_bf16 v[16:31], v[146:149], v[72:75], v[16:31]
	ds_read_b64_tr_b16 v[72:73], v191 offset:0x600
	ds_read_b64_tr_b16 v[74:75], v191 offset:0xe00
	v_add_f32_e32 v192, v100, v192
	v_add_f32_e32 v192, v101, v192
	s_waitcnt lgkmcnt(6)
	v_mfma_f32_32x32x16_bf16 v[16:31], v[150:153], v[76:79], v[16:31]
	ds_read_b64_tr_b16 v[76:77], v191 offset:0x1600
	ds_read_b64_tr_b16 v[78:79], v191 offset:0x1e00
	v_add_f32_e32 v192, v102, v192
	v_add_f32_e32 v192, v103, v192
	s_waitcnt lgkmcnt(6)
	v_mfma_f32_32x32x16_bf16 v[16:31], v[64:67], v[234:237], v[16:31]
	ds_read_b64_tr_b16 v[234:235], v191 offset:0x2600
	ds_read_b64_tr_b16 v[236:237], v191 offset:0x2e00
	v_add_f32_e32 v192, v104, v192
	v_add_f32_e32 v192, v105, v192
	s_waitcnt lgkmcnt(6)
	v_mfma_f32_32x32x16_bf16 v[16:31], v[68:71], v[238:241], v[16:31]
	ds_read_b64_tr_b16 v[238:239], v191 offset:0x3600
	ds_read_b64_tr_b16 v[240:241], v191 offset:0x3e00
	v_add_f32_e32 v192, v106, v192
	v_add_f32_e32 v192, v107, v192
	s_waitcnt vmcnt(0)
	s_barrier
	ds_read_b128 v[154:157], v224 offset:32768
	ds_read_b128 v[158:161], v224 offset:40960
	ds_read_b128 v[162:165], v225 offset:32768
	ds_read_b128 v[242:245], v225 offset:40960
	s_waitcnt lgkmcnt(10)
	v_mfma_f32_32x32x16_bf16 v[0:15], v[146:149], v[72:75], v[0:15]
	v_add_f32_e32 v192, v108, v192
	v_add_f32_e32 v192, v109, v192
	v_cvt_pk_bf16_f32 v146, v96, v97
	v_cvt_pk_bf16_f32 v147, v98, v99
	v_cvt_pk_bf16_f32 v148, v100, v101
	v_cvt_pk_bf16_f32 v149, v102, v103
	s_waitcnt lgkmcnt(8)
	v_mfma_f32_32x32x16_bf16 v[0:15], v[150:153], v[76:79], v[0:15]
	v_add_f32_e32 v192, v110, v192
	v_add_f32_e32 v192, v111, v192
	v_cvt_pk_bf16_f32 v150, v104, v105
	v_cvt_pk_bf16_f32 v151, v106, v107
	v_cvt_pk_bf16_f32 v152, v108, v109
	v_cvt_pk_bf16_f32 v153, v110, v111
	v_permlane32_swap_b32_e32 v146, v148
	v_permlane32_swap_b32_e32 v147, v149
	s_waitcnt lgkmcnt(6)
	v_mfma_f32_32x32x16_bf16 v[0:15], v[64:67], v[234:237], v[0:15]
	v_permlane32_swap_b32_e32 v150, v152
	v_permlane32_swap_b32_e32 v151, v153
	s_waitcnt lgkmcnt(4)
	v_mfma_f32_32x32x16_bf16 v[0:15], v[68:71], v[238:241], v[0:15]
	ds_read_b128 v[234:237], v226 offset:32768
	ds_read_b128 v[238:241], v226 offset:40960
	s_add_i32 s9, s7, -1
	s_lshl_b32 s9, s9, 15
	s_add_u32 s26, s10, s9
	s_addc_u32 s27, s11, 0
	s_add_u32 m0, vcc_lo, vcc_hi
	s_add_u32 m0, m0, 0x4000
	s_nop 0
	global_load_lds_dwordx4 v218, s[26:27]
	v_exp_f32_e32 v80, v80
	v_exp_f32_e32 v83, v83
	s_waitcnt lgkmcnt(5)
	v_mfma_f32_32x32x16_bf16 v[96:111], v[154:157], v[142:145], 0
	ds_read_b128 v[154:157], v227 offset:32768
	s_add_u32 s26, s26, 0x4000
	s_addc_u32 s27, s27, 0
	s_add_u32 m0, m0, 0x2000
	s_nop 0
	global_load_lds_dwordx4 v218, s[26:27]
	v_exp_f32_e32 v84, v84
	v_exp_f32_e32 v85, v85
	s_waitcnt lgkmcnt(5)
	v_mfma_f32_32x32x16_bf16 v[64:79], v[158:161], v[142:145], 0
	ds_read_b128 v[158:161], v227 offset:40960
	s_add_u32 s26, s28, s9
	s_addc_u32 s27, s29, 0
	s_add_u32 m0, vcc_lo, 0xc000
	s_nop 0
	global_load_lds_dwordx4 v233, s[26:27]
	v_exp_f32_e32 v86, v86
	v_exp_f32_e32 v87, v87
	s_waitcnt lgkmcnt(5)
	v_mfma_f32_32x32x16_bf16 v[96:111], v[162:165], v[138:141], v[96:111]
	ds_read_b128 v[162:165], v228 offset:32768
	s_add_u32 s26, s26, 0x4000
	s_addc_u32 s27, s27, 0
	s_add_u32 m0, m0, 0x2000
	s_nop 0
	global_load_lds_dwordx4 v233, s[26:27]
	v_exp_f32_e32 v88, v88
	v_exp_f32_e32 v89, v89
	s_waitcnt lgkmcnt(5)
	v_mfma_f32_32x32x16_bf16 v[64:79], v[242:245], v[138:141], v[64:79]
	v_exp_f32_e32 v90, v90
	v_exp_f32_e32 v91, v91
	s_waitcnt lgkmcnt(4)
	v_mfma_f32_32x32x16_bf16 v[96:111], v[234:237], v[134:137], v[96:111]
	ds_read_b128 v[234:237], v228 offset:40960
	v_exp_f32_e32 v92, v92
	v_exp_f32_e32 v93, v93
	s_waitcnt lgkmcnt(4)
	v_mfma_f32_32x32x16_bf16 v[64:79], v[238:241], v[134:137], v[64:79]
	ds_read_b128 v[238:241], v229 offset:32768
	v_exp_f32_e32 v94, v94
	v_exp_f32_e32 v95, v95
	s_waitcnt lgkmcnt(4)
	v_mfma_f32_32x32x16_bf16 v[96:111], v[154:157], v[130:133], v[96:111]
	ds_read_b128 v[154:157], v229 offset:40960
	v_exp_f32_e32 v166, v81
	v_exp_f32_e32 v167, v82
	s_waitcnt lgkmcnt(4)
; #define SBAR() __builtin_amdgcn_sched_barrier(0)
; #define SLOAD(i, k0) do { sr_[i].vs0 = *reinterpret_cast<const bf16x8*>(&Vh[(size_t)((k0) + sr) * ldk + sc]); sr_[i].vs1 = *reinterpret_cast<const bf16x8*>(&Vh[(size_t)((k0) + 32 + sr) * ldk + sc]); \
;     sr_[i].ks0 = *reinterpret_cast<const bf16x8*>(&Kh[(size_t)((k0) + sr) * ldk + sc]); sr_[i].ks1 = *reinterpret_cast<const bf16x8*>(&Kh[(size_t)((k0) + 32 + sr) * ldk + sc]); } while (0)
; #define SWAIT() asm volatile("s_waitcnt vmcnt(4)" ::: "memory")
; DEVINL void partialSM_bal(f32x16& p0, float& ps, bf16x8& pa0, bf16x8& pa1) {
; #pragma unroll
;   for (int r = 0; r < 16; ++r) p0[r] = __builtin_amdgcn_exp2f(p0[r]);
;   float s = 0;
; #pragma unroll
;   for (int r = 0; r < 16; ++r) s += p0[r];
;   ps = s;
;   PK4F(p0, 0, pa0); PK4F(p0, 8, pa1);
; }
; DEVINL void finishSM_bal(f32x16& p1, float ps, float& l_reg, bf16x8& pa2, bf16x8& pa3) {
; #pragma unroll
;   for (int r = 0; r < 16; ++r) p1[r] = __builtin_amdgcn_exp2f(p1[r]);
; #pragma unroll
;   for (int r = 0; r < 16; ++r) ps += p1[r];
;   { auto rr = __builtin_amdgcn_permlane32_swap(__float_as_uint(ps), __float_as_uint(ps), false, false);
;     ps = __uint_as_float(rr[0]) + __uint_as_float(rr[1]); }
;   l_reg += ps;
;   PK4F(p1, 0, pa2); PK4F(p1, 8, pa3);
; }
; template <int ND0>
; DEVINL void qkt(f32x16& p0, f32x16& p1, const bf16* Ks, const bf16x8* qr, int r32, int hi, int colbase) {
;   p0 = f32x16{}; p1 = f32x16{};
;   __builtin_amdgcn_iglp_opt(1);
; #pragma unroll
;   for (int d0 = 0; d0 < ND0; ++d0) { int cb = (colbase + d0 * 16 + hi * 8) * 2;
;     bf16x8 b0 = *reinterpret_cast<const bf16x8*>((const char*)Ks + KSWZ(r32, cb));
;     bf16x8 b1 = *reinterpret_cast<const bf16x8*>((const char*)Ks + KSWZ(32 + r32, cb));
;     p0 = __builtin_amdgcn_mfma_f32_32x32x16_bf16(b0, qr[d0], p0, 0, 0, 0);
;     p1 = __builtin_amdgcn_mfma_f32_32x32x16_bf16(b1, qr[d0], p1, 0, 0, 0); }
; }
; template <bool DIFF, bool FAST> ...
;     ...
;     __syncthreads();
;     SBAR(); qkt<ND0>(pA0, pA1, K_lds, qr, r32, hi, colbase);
;     finishSM_bal(pB1, psB, l_reg, pa2, pa3); SBAR();
;     SLOAD(SE, (j + 3 < NT ? j + 3 : NT - 1) * KVBLK);     SBAR();
;     pv_d0(o, vb0 + (int)SHM_V, paB0, paB1, pa2, pa3); partialSM_bal(pA0, psA, paA0, paA1);
;     __syncthreads(); SWAIT(); SWRITE(1, SO);
;     __syncthreads();
	v_mfma_f32_32x32x16_bf16 v[64:79], v[158:161], v[130:133], v[64:79]
	ds_read_b128 v[158:161], v231 offset:32768
	v_add_f32_e32 v81, v80, v192
	v_add_f32_e32 v81, v166, v81
	v_add_f32_e32 v81, v167, v81
	v_add_f32_e32 v81, v83, v81
	s_waitcnt lgkmcnt(4)
	v_mfma_f32_32x32x16_bf16 v[96:111], v[162:165], v[126:129], v[96:111]
	ds_read_b128 v[162:165], v231 offset:40960
	v_add_f32_e32 v81, v84, v81
	v_add_f32_e32 v81, v85, v81
	v_add_f32_e32 v81, v86, v81
	v_add_f32_e32 v81, v87, v81
	s_waitcnt lgkmcnt(4)
	v_mfma_f32_32x32x16_bf16 v[64:79], v[234:237], v[126:129], v[64:79]
	ds_read_b128 v[234:237], v230 offset:32768
	v_add_f32_e32 v81, v88, v81
	v_add_f32_e32 v81, v89, v81
	v_add_f32_e32 v81, v90, v81
	v_add_f32_e32 v81, v91, v81
	s_waitcnt lgkmcnt(4)
	v_mfma_f32_32x32x16_bf16 v[96:111], v[238:241], v[122:125], v[96:111]
	ds_read_b128 v[238:241], v230 offset:40960
	v_add_f32_e32 v81, v92, v81
	v_add_f32_e32 v81, v93, v81
	v_add_f32_e32 v81, v94, v81
	v_add_f32_e32 v81, v95, v81
	s_waitcnt lgkmcnt(4)
	v_mfma_f32_32x32x16_bf16 v[64:79], v[154:157], v[122:125], v[64:79]
	v_mov_b32_e32 v82, v81
	s_nop 1
	v_permlane32_swap_b32_e32 v81, v82
	v_add_f32_e32 v81, v81, v82
	s_waitcnt lgkmcnt(3)
	v_mfma_f32_32x32x16_bf16 v[96:111], v[158:161], v[118:121], v[96:111]
	v_cvt_pk_bf16_f32 v82, v80, v166
	v_cvt_pk_bf16_f32 v83, v167, v83
	v_cvt_pk_bf16_f32 v84, v84, v85
	v_cvt_pk_bf16_f32 v85, v86, v87
	s_waitcnt lgkmcnt(2)
	v_mfma_f32_32x32x16_bf16 v[64:79], v[162:165], v[118:121], v[64:79]
	v_cvt_pk_bf16_f32 v86, v88, v89
	v_cvt_pk_bf16_f32 v87, v90, v91
	v_cvt_pk_bf16_f32 v88, v92, v93
	v_cvt_pk_bf16_f32 v89, v94, v95
	s_waitcnt lgkmcnt(1)
	v_mfma_f32_32x32x16_bf16 v[96:111], v[234:237], v[114:117], v[96:111]
	v_permlane32_swap_b32_e32 v82, v84
	v_permlane32_swap_b32_e32 v83, v85
	v_permlane32_swap_b32_e32 v86, v88
	v_permlane32_swap_b32_e32 v87, v89
	s_waitcnt lgkmcnt(0)
	v_mfma_f32_32x32x16_bf16 v[64:79], v[238:241], v[114:117], v[64:79]
	ds_read_b64_tr_b16 v[90:91], v222 offset:0
	ds_read_b64_tr_b16 v[92:93], v222 offset:0x800
	ds_read_b64_tr_b16 v[234:235], v222 offset:0x1000
	ds_read_b64_tr_b16 v[236:237], v222 offset:0x1800
	ds_read_b64_tr_b16 v[238:239], v222 offset:0x2000
	ds_read_b64_tr_b16 v[240:241], v222 offset:0x2800
	ds_read_b64_tr_b16 v[242:243], v222 offset:0x3000
	ds_read_b64_tr_b16 v[244:245], v222 offset:0x3800
	s_waitcnt lgkmcnt(6)
	v_mfma_f32_32x32x16_bf16 v[48:63], v[146:149], v[90:93], v[48:63]
	ds_read_b64_tr_b16 v[90:91], v222 offset:0x200
	ds_read_b64_tr_b16 v[92:93], v222 offset:0xa00
	v_exp_f32_e32 v96, v96
	v_exp_f32_e32 v97, v97
	s_waitcnt lgkmcnt(6)
	v_mfma_f32_32x32x16_bf16 v[48:63], v[150:153], v[234:237], v[48:63]
	ds_read_b64_tr_b16 v[234:235], v222 offset:0x1200
	ds_read_b64_tr_b16 v[236:237], v222 offset:0x1a00
	v_exp_f32_e32 v98, v98
	v_exp_f32_e32 v99, v99
	s_waitcnt lgkmcnt(6)
	v_mfma_f32_32x32x16_bf16 v[48:63], v[82:85], v[238:241], v[48:63]
	ds_read_b64_tr_b16 v[238:239], v222 offset:0x2200
	ds_read_b64_tr_b16 v[240:241], v222 offset:0x2a00
	v_exp_f32_e32 v100, v100
	v_exp_f32_e32 v101, v101
	s_waitcnt lgkmcnt(6)
	v_mfma_f32_32x32x16_bf16 v[48:63], v[86:89], v[242:245], v[48:63]
	ds_read_b64_tr_b16 v[242:243], v222 offset:0x3200
	ds_read_b64_tr_b16 v[244:245], v222 offset:0x3a00
	v_exp_f32_e32 v102, v102
	v_exp_f32_e32 v103, v103
	s_waitcnt lgkmcnt(6)
	v_mfma_f32_32x32x16_bf16 v[32:47], v[146:149], v[90:93], v[32:47]
	ds_read_b64_tr_b16 v[90:91], v222 offset:0x400
	ds_read_b64_tr_b16 v[92:93], v222 offset:0xc00
	v_exp_f32_e32 v104, v104
	v_exp_f32_e32 v105, v105
	s_waitcnt lgkmcnt(6)
	v_mfma_f32_32x32x16_bf16 v[32:47], v[150:153], v[234:237], v[32:47]
	ds_read_b64_tr_b16 v[234:235], v222 offset:0x1400
	ds_read_b64_tr_b16 v[236:237], v222 offset:0x1c00
	v_exp_f32_e32 v106, v106
	v_exp_f32_e32 v107, v107
	s_waitcnt lgkmcnt(6)
	v_mfma_f32_32x32x16_bf16 v[32:47], v[82:85], v[238:241], v[32:47]
	ds_read_b64_tr_b16 v[238:239], v222 offset:0x2400
	ds_read_b64_tr_b16 v[240:241], v222 offset:0x2c00
	v_exp_f32_e32 v108, v108
	v_exp_f32_e32 v196, v109
	v_add_f32_e32 v194, 0, v96
	v_add_f32_e32 v194, v97, v194
	s_waitcnt lgkmcnt(6)
	v_mfma_f32_32x32x16_bf16 v[32:47], v[86:89], v[242:245], v[32:47]
	ds_read_b64_tr_b16 v[242:243], v222 offset:0x3400
	ds_read_b64_tr_b16 v[244:245], v222 offset:0x3c00
	v_exp_f32_e32 v192, v110
	v_exp_f32_e32 v80, v111
	v_add_f32_e32 v194, v98, v194
	v_add_f32_e32 v194, v99, v194
	s_waitcnt lgkmcnt(6)
	v_mfma_f32_32x32x16_bf16 v[16:31], v[146:149], v[90:93], v[16:31]
	ds_read_b64_tr_b16 v[90:91], v222 offset:0x600
	ds_read_b64_tr_b16 v[92:93], v222 offset:0xe00
	v_add_f32_e32 v194, v100, v194
	v_add_f32_e32 v194, v101, v194
	s_waitcnt lgkmcnt(6)
	v_mfma_f32_32x32x16_bf16 v[16:31], v[150:153], v[234:237], v[16:31]
	ds_read_b64_tr_b16 v[234:235], v222 offset:0x1600
	ds_read_b64_tr_b16 v[236:237], v222 offset:0x1e00
	v_add_f32_e32 v194, v102, v194
	v_add_f32_e32 v194, v103, v194
	s_waitcnt lgkmcnt(6)
	v_mfma_f32_32x32x16_bf16 v[16:31], v[82:85], v[238:241], v[16:31]
	ds_read_b64_tr_b16 v[238:239], v222 offset:0x2600
	ds_read_b64_tr_b16 v[240:241], v222 offset:0x2e00
	v_add_f32_e32 v194, v104, v194
	v_add_f32_e32 v194, v105, v194
	s_waitcnt lgkmcnt(6)
	v_mfma_f32_32x32x16_bf16 v[16:31], v[86:89], v[242:245], v[16:31]
	ds_read_b64_tr_b16 v[242:243], v222 offset:0x3600
	ds_read_b64_tr_b16 v[244:245], v222 offset:0x3e00
	v_add_f32_e32 v194, v106, v194
	v_add_f32_e32 v194, v107, v194
	s_waitcnt vmcnt(0)
	s_barrier
	ds_read_b128 v[170:173], v224 offset:49152
	ds_read_b128 v[174:177], v224 offset:57344
	ds_read_b128 v[178:181], v225 offset:49152
	ds_read_b128 v[182:185], v225 offset:57344
	s_waitcnt lgkmcnt(10)
	v_mfma_f32_32x32x16_bf16 v[0:15], v[146:149], v[90:93], v[0:15]
	v_add_f32_e32 v194, v108, v194
	v_cvt_pk_bf16_f32 v146, v96, v97
	v_cvt_pk_bf16_f32 v147, v98, v99
	v_cvt_pk_bf16_f32 v148, v100, v101
	v_cvt_pk_bf16_f32 v149, v102, v103
	s_waitcnt lgkmcnt(8)
	v_mfma_f32_32x32x16_bf16 v[0:15], v[150:153], v[234:237], v[0:15]
	v_cvt_pk_bf16_f32 v150, v104, v105
	v_cvt_pk_bf16_f32 v151, v106, v107
	v_cvt_pk_bf16_f32 v152, v108, v196
	v_cvt_pk_bf16_f32 v153, v192, v80
	v_permlane32_swap_b32_e32 v146, v148
	v_permlane32_swap_b32_e32 v147, v149
	s_waitcnt lgkmcnt(6)
	v_mfma_f32_32x32x16_bf16 v[0:15], v[82:85], v[238:241], v[0:15]
	v_permlane32_swap_b32_e32 v150, v152
	v_permlane32_swap_b32_e32 v151, v153
	v_pk_add_f32 v[82:83], v[196:197], v[194:195]
	v_pk_add_f32 v[82:83], v[192:193], v[82:83]
	v_pk_add_f32 v[194:195], v[80:81], v[82:83]
	v_xor_b32_e32 v191, 0x10000, v191
	v_xor_b32_e32 v222, 0x10000, v222
	s_xor_b32 vcc_hi, vcc_hi, 0x10000
	s_waitcnt lgkmcnt(4)
	v_mfma_f32_32x32x16_bf16 v[0:15], v[86:89], v[242:245], v[0:15]
	s_add_i32 s9, s7, 2
	s_add_i32 s7, s7, -1
	v_mov_b32_e32 v193, v195
	s_cmp_ge_i32 s7, s6
	s_mov_b32 s7, s9
	s_cbranch_scc0 .Lattn_gqa_top
	s_waitcnt lgkmcnt(0)
	s_branch .LBB0_566

; #define SBAR() __builtin_amdgcn_sched_barrier(0)
; #define SLOAD(i, k0) do { sr_[i].vs0 = *reinterpret_cast<const bf16x8*>(&Vh[(size_t)((k0) + sr) * ldk + sc]); sr_[i].vs1 = *reinterpret_cast<const bf16x8*>(&Vh[(size_t)((k0) + 32 + sr) * ldk + sc]); \
;     sr_[i].ks0 = *reinterpret_cast<const bf16x8*>(&Kh[(size_t)((k0) + sr) * ldk + sc]); sr_[i].ks1 = *reinterpret_cast<const bf16x8*>(&Kh[(size_t)((k0) + 32 + sr) * ldk + sc]); } while (0)
; #define SWRITE(b, i) do { *(bf16x8*)((char*)V_lds + (b) * SHM_V + vst0) = sr_[i].vs0;          \
;     *(bf16x8*)((char*)V_lds + (b) * SHM_V + vst1) = sr_[i].vs1; int kc = sc * 2;               \
;     *(bf16x8*)((char*)K_lds + (b) * SHM_K + KSWZ(sr, kc)) = sr_[i].ks0;                       \
;     *(bf16x8*)((char*)K_lds + (b) * SHM_K + KSWZ(32 + sr, kc)) = sr_[i].ks1; } while (0)
; #define SWAIT() asm volatile("s_waitcnt vmcnt(4)" ::: "memory")
; template <int ND0>
; DEVINL void qkt(f32x16& p0, f32x16& p1, const bf16* Ks, const bf16x8* qr, int r32, int hi, int colbase) {
;   p0 = f32x16{}; p1 = f32x16{};
;   __builtin_amdgcn_iglp_opt(1);
; #pragma unroll
;   for (int d0 = 0; d0 < ND0; ++d0) { int cb = (colbase + d0 * 16 + hi * 8) * 2;
;     bf16x8 b0 = *reinterpret_cast<const bf16x8*>((const char*)Ks + KSWZ(r32, cb));
;     bf16x8 b1 = *reinterpret_cast<const bf16x8*>((const char*)Ks + KSWZ(32 + r32, cb));
;     p0 = __builtin_amdgcn_mfma_f32_32x32x16_bf16(b0, qr[d0], p0, 0, 0, 0);
;     p1 = __builtin_amdgcn_mfma_f32_32x32x16_bf16(b1, qr[d0], p1, 0, 0, 0); }
; }
; template <bool DIFF, bool FAST> ...
;     ...
;   for (int j = 1; j + 1 < NT; j += 2) {
;     SBAR(); qkt<ND0>(pB0, pB1, (bf16*)((char*)K_lds + SHM_K), qr, r32, hi, colbase);
;     finishSM_bal(pA1, psA, l_reg, pa2, pa3); SBAR();
;     SLOAD(SO, (j + 2) * KVBLK); SBAR();
;     pv_d0(o, vb0, paA0, paA1, pa2, pa3); partialSM_bal(pB0, psB, paB0, paB1);
;     __syncthreads(); SWAIT(); SWRITE(0, SE);
.LBB0_607:
	v_readfirstlane_b32 vcc_lo, v182
	s_lshr_b32 vcc_lo, vcc_lo, 6
	s_lshl_b32 vcc_lo, vcc_lo, 10
	s_mov_b32 vcc_hi, 0x10000
	v_lshrrev_b32_e32 v213, 4, v182
	v_and_b32_e32 v190, 15, v213
	v_xor_b32_e32 v190, v190, v182
	v_and_b32_e32 v190, 15, v190
	v_lshlrev_b32_e32 v213, 11, v213
	v_lshl_add_u32 v213, v190, 4, v213
	v_bfe_u32 v184, v182, 2, 2
	v_bfe_u32 v190, v182, 7, 1
	v_lshl_or_b32 v184, v190, 2, v184
	v_bfe_u32 v190, v182, 4, 1
	v_lshl_or_b32 v184, v190, 3, v184
	v_bfe_u32 v190, v182, 8, 1
	v_lshl_or_b32 v184, v190, 4, v184
	v_lshlrev_b32_e32 v184, 11, v184
	v_and_b32_e32 v190, 3, v182
	v_lshl_or_b32 v184, v190, 4, v184
	v_bfe_u32 v190, v182, 5, 2
	v_lshl_or_b32 v184, v190, 6, v184
	s_waitcnt vmcnt(0)
	ds_read_b128 v[154:157], v194 offset:49152
	ds_read_b128 v[158:161], v194 offset:57344
	ds_read_b128 v[162:165], v197 offset:49152
	ds_read_b128 v[166:169], v197 offset:57344
.Lattn_diff_top:
	ds_read_b128 v[214:217], v196 offset:49152
	ds_read_b128 v[218:221], v196 offset:57344
	s_add_i32 s9, s7, -2
	s_lshl_b32 s9, s9, 17
	s_add_u32 s10, s18, s9
	s_addc_u32 s11, s19, 0
	s_add_u32 m0, vcc_lo, vcc_hi
	s_nop 0
	global_load_lds_dwordx4 v184, s[10:11]
	v_exp_f32_e32 v64, v64
	v_exp_f32_e32 v65, v65
	v_exp_f32_e32 v66, v66
	s_waitcnt lgkmcnt(5)
	v_mfma_f32_32x32x16_bf16 v[96:111], v[154:157], v[126:129], 0
	ds_read_b128 v[154:157], v195 offset:49152
	s_add_u32 s10, s10, 0x10000
	s_addc_u32 s11, s11, 0
	s_add_u32 m0, m0, 0x2000
	s_nop 0
	global_load_lds_dwordx4 v184, s[10:11]
	v_exp_f32_e32 v67, v67
	v_exp_f32_e32 v68, v68
	v_exp_f32_e32 v69, v69
	s_waitcnt lgkmcnt(5)
	v_mfma_f32_32x32x16_bf16 v[80:95], v[158:161], v[126:129], 0
	ds_read_b128 v[158:161], v195 offset:57344
	s_add_u32 s10, s16, s9
	s_addc_u32 s11, s17, 0
	s_add_u32 m0, vcc_lo, 0x8000
	s_nop 0
	global_load_lds_dwordx4 v213, s[10:11]
	v_exp_f32_e32 v70, v70
	v_exp_f32_e32 v71, v71
	v_exp_f32_e32 v72, v72
	s_waitcnt lgkmcnt(5)
	v_mfma_f32_32x32x16_bf16 v[96:111], v[162:165], v[122:125], v[96:111]
	s_add_u32 s10, s10, 0x10000
	s_addc_u32 s11, s11, 0
	s_add_u32 m0, m0, 0x2000
	s_nop 0
	global_load_lds_dwordx4 v213, s[10:11]
	v_exp_f32_e32 v73, v73
	v_exp_f32_e32 v74, v74
	v_exp_f32_e32 v75, v75
	s_waitcnt lgkmcnt(4)
	v_mfma_f32_32x32x16_bf16 v[80:95], v[166:169], v[122:125], v[80:95]
	v_exp_f32_e32 v76, v76
	v_exp_f32_e32 v77, v77
	v_exp_f32_e32 v78, v78
	s_waitcnt lgkmcnt(3)
	v_mfma_f32_32x32x16_bf16 v[96:111], v[214:217], v[118:121], v[96:111]
	v_exp_f32_e32 v79, v79
	v_add_f32_e32 v177, v174, v64
	v_add_f32_e32 v177, v65, v177
	v_add_f32_e32 v177, v66, v177
	v_add_f32_e32 v177, v67, v177
	v_add_f32_e32 v177, v68, v177
	s_waitcnt lgkmcnt(2)
	v_mfma_f32_32x32x16_bf16 v[80:95], v[218:221], v[118:121], v[80:95]
	v_add_f32_e32 v177, v69, v177
	v_add_f32_e32 v177, v70, v177
	v_add_f32_e32 v177, v71, v177
	v_add_f32_e32 v177, v72, v177
	v_add_f32_e32 v177, v73, v177
	v_add_f32_e32 v177, v74, v177
	v_add_f32_e32 v177, v75, v177
	s_waitcnt lgkmcnt(1)
	v_mfma_f32_32x32x16_bf16 v[96:111], v[154:157], v[114:117], v[96:111]
	v_add_f32_e32 v177, v76, v177
	v_add_f32_e32 v177, v77, v177
	v_add_f32_e32 v177, v78, v177
	v_add_f32_e32 v177, v79, v177
	v_cvt_pk_bf16_f32 v64, v64, v65
	v_cvt_pk_bf16_f32 v65, v66, v67
	v_cvt_pk_bf16_f32 v66, v68, v69
	s_waitcnt lgkmcnt(0)
	v_mfma_f32_32x32x16_bf16 v[80:95], v[158:161], v[114:117], v[80:95]
	v_cvt_pk_bf16_f32 v67, v70, v71
	v_cvt_pk_bf16_f32 v68, v72, v73
	v_cvt_pk_bf16_f32 v69, v74, v75
	v_cvt_pk_bf16_f32 v70, v76, v77
	v_cvt_pk_bf16_f32 v71, v78, v79
	v_mov_b32_e32 v175, v177
	v_permlane32_swap_b32_e32 v64, v66
	v_permlane32_swap_b32_e32 v65, v67
	v_permlane32_swap_b32_e32 v68, v70
	v_permlane32_swap_b32_e32 v69, v71
	v_permlane32_swap_b32_e32 v177, v175
	ds_read_b64_tr_b16 v[72:73], v171 offset:0
	ds_read_b64_tr_b16 v[74:75], v171 offset:0x800
	ds_read_b64_tr_b16 v[76:77], v171 offset:0x1000
	ds_read_b64_tr_b16 v[78:79], v171 offset:0x1800
	ds_read_b64_tr_b16 v[214:215], v171 offset:0x2000
	ds_read_b64_tr_b16 v[216:217], v171 offset:0x2800
	ds_read_b64_tr_b16 v[218:219], v171 offset:0x3000
	ds_read_b64_tr_b16 v[220:221], v171 offset:0x3800
	s_waitcnt lgkmcnt(6)
	v_mfma_f32_32x32x16_bf16 v[48:63], v[130:133], v[72:75], v[48:63]
	ds_read_b64_tr_b16 v[72:73], v171 offset:0x200
	ds_read_b64_tr_b16 v[74:75], v171 offset:0xa00
	v_exp_f32_e32 v96, v96
	v_exp_f32_e32 v97, v97
	s_waitcnt lgkmcnt(6)
	v_mfma_f32_32x32x16_bf16 v[48:63], v[134:137], v[76:79], v[48:63]
	ds_read_b64_tr_b16 v[76:77], v171 offset:0x1200
	ds_read_b64_tr_b16 v[78:79], v171 offset:0x1a00
	v_exp_f32_e32 v98, v98
	v_exp_f32_e32 v99, v99
	s_waitcnt lgkmcnt(6)
	v_mfma_f32_32x32x16_bf16 v[48:63], v[64:67], v[214:217], v[48:63]
	ds_read_b64_tr_b16 v[214:215], v171 offset:0x2200
	ds_read_b64_tr_b16 v[216:217], v171 offset:0x2a00
	v_exp_f32_e32 v100, v100
	v_exp_f32_e32 v101, v101
	s_waitcnt lgkmcnt(6)
	v_mfma_f32_32x32x16_bf16 v[48:63], v[68:71], v[218:221], v[48:63]
	ds_read_b64_tr_b16 v[218:219], v171 offset:0x3200
	ds_read_b64_tr_b16 v[220:221], v171 offset:0x3a00
	v_exp_f32_e32 v102, v102
	v_exp_f32_e32 v103, v103
	s_waitcnt lgkmcnt(6)
	v_mfma_f32_32x32x16_bf16 v[32:47], v[130:133], v[72:75], v[32:47]
	ds_read_b64_tr_b16 v[72:73], v171 offset:0x400
	ds_read_b64_tr_b16 v[74:75], v171 offset:0xc00
	v_exp_f32_e32 v104, v104
	v_exp_f32_e32 v105, v105
	s_waitcnt lgkmcnt(6)
	v_mfma_f32_32x32x16_bf16 v[32:47], v[134:137], v[76:79], v[32:47]
	ds_read_b64_tr_b16 v[76:77], v171 offset:0x1400
	ds_read_b64_tr_b16 v[78:79], v171 offset:0x1c00
	v_exp_f32_e32 v106, v106
	v_exp_f32_e32 v107, v107
	s_waitcnt lgkmcnt(6)
; #define SBAR() __builtin_amdgcn_sched_barrier(0)
; #define SLOAD(i, k0) do { sr_[i].vs0 = *reinterpret_cast<const bf16x8*>(&Vh[(size_t)((k0) + sr) * ldk + sc]); sr_[i].vs1 = *reinterpret_cast<const bf16x8*>(&Vh[(size_t)((k0) + 32 + sr) * ldk + sc]); \
;     sr_[i].ks0 = *reinterpret_cast<const bf16x8*>(&Kh[(size_t)((k0) + sr) * ldk + sc]); sr_[i].ks1 = *reinterpret_cast<const bf16x8*>(&Kh[(size_t)((k0) + 32 + sr) * ldk + sc]); } while (0)
; #define SWAIT() asm volatile("s_waitcnt vmcnt(4)" ::: "memory")
; template <int OFF> DEVINL s16x4 tr_read(int vb) {
;   s16x4 r; asm volatile("ds_read_b64_tr_b16 %0, %1 offset:%2" : "=&v"(r) : "v"(vb), "i"(OFF) : "memory"); return r;
; }
; template <int D0> DEVINL void pv_one(f32x16& od, int vb, bf16x8 pa0, bf16x8 pa1, bf16x8 pa2, bf16x8 pa3) {
;   const s16x4 l0 = tr_read<v_rd_off(D0, 0, 0)>(vb), h0 = tr_read<v_rd_off(D0, 0, 1)>(vb), l1 = tr_read<v_rd_off(D0, 1, 0)>(vb), h1 = tr_read<v_rd_off(D0, 1, 1)>(vb);
;   const s16x4 l2 = tr_read<v_rd_off(D0, 2, 0)>(vb), h2 = tr_read<v_rd_off(D0, 2, 1)>(vb), l3 = tr_read<v_rd_off(D0, 3, 0)>(vb), h3 = tr_read<v_rd_off(D0, 3, 1)>(vb);
;   asm volatile("s_waitcnt lgkmcnt(0)" ::: "memory"); SBAR();
;     ...
;   od = __builtin_amdgcn_mfma_f32_32x32x16_bf16(pa0, PK(l0, h0), od, 0, 0, 0);
;   od = __builtin_amdgcn_mfma_f32_32x32x16_bf16(pa1, PK(l1, h1), od, 0, 0, 0);
;   od = __builtin_amdgcn_mfma_f32_32x32x16_bf16(pa2, PK(l2, h2), od, 0, 0, 0);
;   od = __builtin_amdgcn_mfma_f32_32x32x16_bf16(pa3, PK(l3, h3), od, 0, 0, 0);
;     ...
; }
; DEVINL void pv_d0(f32x16* o, int vb, bf16x8 pa0, bf16x8 pa1, bf16x8 pa2, bf16x8 pa3) {
;   pv_one<0>(o[0], vb, pa0, pa1, pa2, pa3); pv_one<1>(o[1], vb, pa0, pa1, pa2, pa3); pv_one<2>(o[2], vb, pa0, pa1, pa2, pa3); pv_one<3>(o[3], vb, pa0, pa1, pa2, pa3);
; }
; template <bool DIFF, bool FAST> ...
;     ...
;     SLOAD(SO, (j + 2) * KVBLK); SBAR();
;     pv_d0(o, vb0, paA0, paA1, pa2, pa3); partialSM_bal(pB0, psB, paB0, paB1);
;     __syncthreads(); SWAIT(); SWRITE(0, SE);
;     __syncthreads();
;     SBAR(); qkt<ND0>(pA0, pA1, K_lds, qr, r32, hi, colbase);
;     finishSM_bal(pB1, psB, l_reg, pa2, pa3); SBAR();
	v_mfma_f32_32x32x16_bf16 v[32:47], v[64:67], v[214:217], v[32:47]
	ds_read_b64_tr_b16 v[214:215], v171 offset:0x2400
	ds_read_b64_tr_b16 v[216:217], v171 offset:0x2c00
	v_exp_f32_e32 v108, v108
	v_exp_f32_e32 v109, v109
	v_add_f32_e32 v172, 0, v96
	v_add_f32_e32 v172, v97, v172
	s_waitcnt lgkmcnt(6)
	v_mfma_f32_32x32x16_bf16 v[32:47], v[68:71], v[218:221], v[32:47]
	ds_read_b64_tr_b16 v[218:219], v171 offset:0x3400
	ds_read_b64_tr_b16 v[220:221], v171 offset:0x3c00
	v_exp_f32_e32 v110, v110
	v_exp_f32_e32 v111, v111
	v_add_f32_e32 v172, v98, v172
	v_add_f32_e32 v172, v99, v172
	s_waitcnt lgkmcnt(6)
	v_mfma_f32_32x32x16_bf16 v[16:31], v[130:133], v[72:75], v[16:31]
	ds_read_b64_tr_b16 v[72:73], v171 offset:0x600
	ds_read_b64_tr_b16 v[74:75], v171 offset:0xe00
	v_add_f32_e32 v172, v100, v172
	v_add_f32_e32 v172, v101, v172
	s_waitcnt lgkmcnt(6)
	v_mfma_f32_32x32x16_bf16 v[16:31], v[134:137], v[76:79], v[16:31]
	ds_read_b64_tr_b16 v[76:77], v171 offset:0x1600
	ds_read_b64_tr_b16 v[78:79], v171 offset:0x1e00
	v_add_f32_e32 v172, v102, v172
	v_add_f32_e32 v172, v103, v172
	s_waitcnt lgkmcnt(6)
	v_mfma_f32_32x32x16_bf16 v[16:31], v[64:67], v[214:217], v[16:31]
	ds_read_b64_tr_b16 v[214:215], v171 offset:0x2600
	ds_read_b64_tr_b16 v[216:217], v171 offset:0x2e00
	v_add_f32_e32 v172, v104, v172
	v_add_f32_e32 v172, v105, v172
	s_waitcnt lgkmcnt(6)
	v_mfma_f32_32x32x16_bf16 v[16:31], v[68:71], v[218:221], v[16:31]
	ds_read_b64_tr_b16 v[218:219], v171 offset:0x3600
	ds_read_b64_tr_b16 v[220:221], v171 offset:0x3e00
	v_add_f32_e32 v172, v106, v172
	v_add_f32_e32 v172, v107, v172
	s_waitcnt vmcnt(0)
	s_barrier
	ds_read_b128 v[138:141], v194 offset:32768
	ds_read_b128 v[142:145], v194 offset:40960
	ds_read_b128 v[146:149], v197 offset:32768
	ds_read_b128 v[222:225], v197 offset:40960
	s_waitcnt lgkmcnt(10)
	v_mfma_f32_32x32x16_bf16 v[0:15], v[130:133], v[72:75], v[0:15]
	v_add_f32_e32 v172, v108, v172
	v_add_f32_e32 v172, v109, v172
	v_cvt_pk_bf16_f32 v130, v96, v97
	v_cvt_pk_bf16_f32 v131, v98, v99
	v_cvt_pk_bf16_f32 v132, v100, v101
	v_cvt_pk_bf16_f32 v133, v102, v103
	s_waitcnt lgkmcnt(8)
	v_mfma_f32_32x32x16_bf16 v[0:15], v[134:137], v[76:79], v[0:15]
	v_add_f32_e32 v172, v110, v172
	v_add_f32_e32 v172, v111, v172
	v_cvt_pk_bf16_f32 v134, v104, v105
	v_cvt_pk_bf16_f32 v135, v106, v107
	v_cvt_pk_bf16_f32 v136, v108, v109
	v_cvt_pk_bf16_f32 v137, v110, v111
	v_permlane32_swap_b32_e32 v130, v132
	v_permlane32_swap_b32_e32 v131, v133
	s_waitcnt lgkmcnt(6)
	v_mfma_f32_32x32x16_bf16 v[0:15], v[64:67], v[214:217], v[0:15]
	v_permlane32_swap_b32_e32 v134, v136
	v_permlane32_swap_b32_e32 v135, v137
	s_waitcnt lgkmcnt(4)
	v_mfma_f32_32x32x16_bf16 v[0:15], v[68:71], v[218:221], v[0:15]
	ds_read_b128 v[214:217], v196 offset:32768
	ds_read_b128 v[218:221], v196 offset:40960
	s_add_i32 s9, s7, -1
	s_lshl_b32 s9, s9, 17
	s_add_u32 s10, s18, s9
	s_addc_u32 s11, s19, 0
	s_add_u32 m0, vcc_lo, vcc_hi
	s_add_u32 m0, m0, 0x4000
	s_nop 0
	global_load_lds_dwordx4 v184, s[10:11]
	v_exp_f32_e32 v80, v80
	v_exp_f32_e32 v83, v83
	v_exp_f32_e32 v84, v84
	v_exp_f32_e32 v85, v85
	s_waitcnt lgkmcnt(5)
	v_mfma_f32_32x32x16_bf16 v[96:111], v[138:141], v[126:129], 0
	ds_read_b128 v[138:141], v195 offset:32768
	s_add_u32 s10, s10, 0x10000
	s_addc_u32 s11, s11, 0
	s_add_u32 m0, m0, 0x2000
	s_nop 0
	global_load_lds_dwordx4 v184, s[10:11]
	v_exp_f32_e32 v86, v86
	v_exp_f32_e32 v87, v87
	v_exp_f32_e32 v88, v88
	v_exp_f32_e32 v89, v89
	s_waitcnt lgkmcnt(5)
	v_mfma_f32_32x32x16_bf16 v[64:79], v[142:145], v[126:129], 0
	ds_read_b128 v[142:145], v195 offset:40960
	s_add_u32 s10, s16, s9
	s_addc_u32 s11, s17, 0
	s_add_u32 m0, vcc_lo, 0xc000
	s_nop 0
	global_load_lds_dwordx4 v213, s[10:11]
	v_exp_f32_e32 v90, v90
	v_exp_f32_e32 v91, v91
	v_exp_f32_e32 v92, v92
	v_exp_f32_e32 v93, v93
	s_waitcnt lgkmcnt(5)
	v_mfma_f32_32x32x16_bf16 v[96:111], v[146:149], v[122:125], v[96:111]
	s_add_u32 s10, s10, 0x10000
	s_addc_u32 s11, s11, 0
	s_add_u32 m0, m0, 0x2000
	s_nop 0
	global_load_lds_dwordx4 v213, s[10:11]
	v_exp_f32_e32 v94, v94
	v_exp_f32_e32 v95, v95
	v_exp_f32_e32 v150, v81
	v_exp_f32_e32 v151, v82
	s_waitcnt lgkmcnt(4)
	v_mfma_f32_32x32x16_bf16 v[64:79], v[222:225], v[122:125], v[64:79]
	v_add_f32_e32 v81, v80, v172
	v_add_f32_e32 v81, v150, v81
	v_add_f32_e32 v81, v151, v81
	v_add_f32_e32 v81, v83, v81
	v_add_f32_e32 v81, v84, v81
	v_add_f32_e32 v81, v85, v81
	v_add_f32_e32 v81, v86, v81
	v_add_f32_e32 v81, v87, v81
	s_waitcnt lgkmcnt(3)
	v_mfma_f32_32x32x16_bf16 v[96:111], v[214:217], v[118:121], v[96:111]
	v_add_f32_e32 v81, v88, v81
	v_add_f32_e32 v81, v89, v81
	v_add_f32_e32 v81, v90, v81
	v_add_f32_e32 v81, v91, v81
	v_add_f32_e32 v81, v92, v81
	v_add_f32_e32 v81, v93, v81
	v_add_f32_e32 v81, v94, v81
	v_add_f32_e32 v81, v95, v81
	s_waitcnt lgkmcnt(2)
	v_mfma_f32_32x32x16_bf16 v[64:79], v[218:221], v[118:121], v[64:79]
	v_mov_b32_e32 v82, v81
	s_nop 1
	v_permlane32_swap_b32_e32 v81, v82
	v_add_f32_e32 v81, v81, v82
	v_cvt_pk_bf16_f32 v82, v80, v150
	v_cvt_pk_bf16_f32 v83, v151, v83
	v_cvt_pk_bf16_f32 v84, v84, v85
	v_cvt_pk_bf16_f32 v85, v86, v87
	s_waitcnt lgkmcnt(1)
; #define SBAR() __builtin_amdgcn_sched_barrier(0)
; #define SLOAD(i, k0) do { sr_[i].vs0 = *reinterpret_cast<const bf16x8*>(&Vh[(size_t)((k0) + sr) * ldk + sc]); sr_[i].vs1 = *reinterpret_cast<const bf16x8*>(&Vh[(size_t)((k0) + 32 + sr) * ldk + sc]); \
;     sr_[i].ks0 = *reinterpret_cast<const bf16x8*>(&Kh[(size_t)((k0) + sr) * ldk + sc]); sr_[i].ks1 = *reinterpret_cast<const bf16x8*>(&Kh[(size_t)((k0) + 32 + sr) * ldk + sc]); } while (0)
; #define SWRITE(b, i) do { *(bf16x8*)((char*)V_lds + (b) * SHM_V + vst0) = sr_[i].vs0;          \
;     *(bf16x8*)((char*)V_lds + (b) * SHM_V + vst1) = sr_[i].vs1; int kc = sc * 2;               \
;     *(bf16x8*)((char*)K_lds + (b) * SHM_K + KSWZ(sr, kc)) = sr_[i].ks0;                       \
;     *(bf16x8*)((char*)K_lds + (b) * SHM_K + KSWZ(32 + sr, kc)) = sr_[i].ks1; } while (0)
; template <int OFF> DEVINL s16x4 tr_read(int vb) {
;   s16x4 r; asm volatile("ds_read_b64_tr_b16 %0, %1 offset:%2" : "=&v"(r) : "v"(vb), "i"(OFF) : "memory"); return r;
; }
; template <int D0> DEVINL void pv_one(f32x16& od, int vb, bf16x8 pa0, bf16x8 pa1, bf16x8 pa2, bf16x8 pa3) {
;   const s16x4 l0 = tr_read<v_rd_off(D0, 0, 0)>(vb), h0 = tr_read<v_rd_off(D0, 0, 1)>(vb), l1 = tr_read<v_rd_off(D0, 1, 0)>(vb), h1 = tr_read<v_rd_off(D0, 1, 1)>(vb);
;   const s16x4 l2 = tr_read<v_rd_off(D0, 2, 0)>(vb), h2 = tr_read<v_rd_off(D0, 2, 1)>(vb), l3 = tr_read<v_rd_off(D0, 3, 0)>(vb), h3 = tr_read<v_rd_off(D0, 3, 1)>(vb);
;   asm volatile("s_waitcnt lgkmcnt(0)" ::: "memory"); SBAR();
;     ...
;   od = __builtin_amdgcn_mfma_f32_32x32x16_bf16(pa0, PK(l0, h0), od, 0, 0, 0);
;   od = __builtin_amdgcn_mfma_f32_32x32x16_bf16(pa1, PK(l1, h1), od, 0, 0, 0);
;   od = __builtin_amdgcn_mfma_f32_32x32x16_bf16(pa2, PK(l2, h2), od, 0, 0, 0);
;   od = __builtin_amdgcn_mfma_f32_32x32x16_bf16(pa3, PK(l3, h3), od, 0, 0, 0);
;     ...
; }
; DEVINL void pv_d0(f32x16* o, int vb, bf16x8 pa0, bf16x8 pa1, bf16x8 pa2, bf16x8 pa3) {
;   pv_one<0>(o[0], vb, pa0, pa1, pa2, pa3); pv_one<1>(o[1], vb, pa0, pa1, pa2, pa3); pv_one<2>(o[2], vb, pa0, pa1, pa2, pa3); pv_one<3>(o[3], vb, pa0, pa1, pa2, pa3);
; }
; template <bool DIFF, bool FAST> ...
;     ...
;     SLOAD(SE, (j + 3 < NT ? j + 3 : NT - 1) * KVBLK);     SBAR();
;     pv_d0(o, vb0 + (int)SHM_V, paB0, paB1, pa2, pa3); partialSM_bal(pA0, psA, paA0, paA1);
;     __syncthreads(); SWAIT(); SWRITE(1, SO);
;     __syncthreads();
	v_mfma_f32_32x32x16_bf16 v[96:111], v[138:141], v[114:117], v[96:111]
	v_cvt_pk_bf16_f32 v86, v88, v89
	v_cvt_pk_bf16_f32 v87, v90, v91
	v_cvt_pk_bf16_f32 v88, v92, v93
	v_cvt_pk_bf16_f32 v89, v94, v95
	v_permlane32_swap_b32_e32 v82, v84
	v_permlane32_swap_b32_e32 v83, v85
	v_permlane32_swap_b32_e32 v86, v88
	v_permlane32_swap_b32_e32 v87, v89
	s_waitcnt lgkmcnt(0)
	v_mfma_f32_32x32x16_bf16 v[64:79], v[142:145], v[114:117], v[64:79]
	ds_read_b64_tr_b16 v[90:91], v192 offset:0
	ds_read_b64_tr_b16 v[92:93], v192 offset:0x800
	ds_read_b64_tr_b16 v[214:215], v192 offset:0x1000
	ds_read_b64_tr_b16 v[216:217], v192 offset:0x1800
	ds_read_b64_tr_b16 v[218:219], v192 offset:0x2000
	ds_read_b64_tr_b16 v[220:221], v192 offset:0x2800
	ds_read_b64_tr_b16 v[222:223], v192 offset:0x3000
	ds_read_b64_tr_b16 v[224:225], v192 offset:0x3800
	s_waitcnt lgkmcnt(6)
	v_mfma_f32_32x32x16_bf16 v[48:63], v[130:133], v[90:93], v[48:63]
	ds_read_b64_tr_b16 v[90:91], v192 offset:0x200
	ds_read_b64_tr_b16 v[92:93], v192 offset:0xa00
	v_exp_f32_e32 v96, v96
	v_exp_f32_e32 v97, v97
	s_waitcnt lgkmcnt(6)
	v_mfma_f32_32x32x16_bf16 v[48:63], v[134:137], v[214:217], v[48:63]
	ds_read_b64_tr_b16 v[214:215], v192 offset:0x1200
	ds_read_b64_tr_b16 v[216:217], v192 offset:0x1a00
	v_exp_f32_e32 v98, v98
	v_exp_f32_e32 v99, v99
	s_waitcnt lgkmcnt(6)
	v_mfma_f32_32x32x16_bf16 v[48:63], v[82:85], v[218:221], v[48:63]
	ds_read_b64_tr_b16 v[218:219], v192 offset:0x2200
	ds_read_b64_tr_b16 v[220:221], v192 offset:0x2a00
	v_exp_f32_e32 v100, v100
	v_exp_f32_e32 v101, v101
	s_waitcnt lgkmcnt(6)
	v_mfma_f32_32x32x16_bf16 v[48:63], v[86:89], v[222:225], v[48:63]
	ds_read_b64_tr_b16 v[222:223], v192 offset:0x3200
	ds_read_b64_tr_b16 v[224:225], v192 offset:0x3a00
	v_exp_f32_e32 v102, v102
	v_exp_f32_e32 v103, v103
	s_waitcnt lgkmcnt(6)
	v_mfma_f32_32x32x16_bf16 v[32:47], v[130:133], v[90:93], v[32:47]
	ds_read_b64_tr_b16 v[90:91], v192 offset:0x400
	ds_read_b64_tr_b16 v[92:93], v192 offset:0xc00
	v_exp_f32_e32 v104, v104
	v_exp_f32_e32 v105, v105
	s_waitcnt lgkmcnt(6)
	v_mfma_f32_32x32x16_bf16 v[32:47], v[134:137], v[214:217], v[32:47]
	ds_read_b64_tr_b16 v[214:215], v192 offset:0x1400
	ds_read_b64_tr_b16 v[216:217], v192 offset:0x1c00
	v_exp_f32_e32 v106, v106
	v_exp_f32_e32 v107, v107
	s_waitcnt lgkmcnt(6)
	v_mfma_f32_32x32x16_bf16 v[32:47], v[82:85], v[218:221], v[32:47]
	ds_read_b64_tr_b16 v[218:219], v192 offset:0x2400
	ds_read_b64_tr_b16 v[220:221], v192 offset:0x2c00
	v_exp_f32_e32 v108, v108
	v_exp_f32_e32 v176, v109
	v_add_f32_e32 v174, 0, v96
	v_add_f32_e32 v174, v97, v174
	s_waitcnt lgkmcnt(6)
	v_mfma_f32_32x32x16_bf16 v[32:47], v[86:89], v[222:225], v[32:47]
	ds_read_b64_tr_b16 v[222:223], v192 offset:0x3400
	ds_read_b64_tr_b16 v[224:225], v192 offset:0x3c00
	v_exp_f32_e32 v172, v110
	v_exp_f32_e32 v80, v111
	v_add_f32_e32 v174, v98, v174
	v_add_f32_e32 v174, v99, v174
	s_waitcnt lgkmcnt(6)
	v_mfma_f32_32x32x16_bf16 v[16:31], v[130:133], v[90:93], v[16:31]
	ds_read_b64_tr_b16 v[90:91], v192 offset:0x600
	ds_read_b64_tr_b16 v[92:93], v192 offset:0xe00
	v_add_f32_e32 v174, v100, v174
	v_add_f32_e32 v174, v101, v174
	s_waitcnt lgkmcnt(6)
	v_mfma_f32_32x32x16_bf16 v[16:31], v[134:137], v[214:217], v[16:31]
	ds_read_b64_tr_b16 v[214:215], v192 offset:0x1600
	ds_read_b64_tr_b16 v[216:217], v192 offset:0x1e00
	v_add_f32_e32 v174, v102, v174
	v_add_f32_e32 v174, v103, v174
	s_waitcnt lgkmcnt(6)
	v_mfma_f32_32x32x16_bf16 v[16:31], v[82:85], v[218:221], v[16:31]
	ds_read_b64_tr_b16 v[218:219], v192 offset:0x2600
	ds_read_b64_tr_b16 v[220:221], v192 offset:0x2e00
	v_add_f32_e32 v174, v104, v174
	v_add_f32_e32 v174, v105, v174
	s_waitcnt lgkmcnt(6)
	v_mfma_f32_32x32x16_bf16 v[16:31], v[86:89], v[222:225], v[16:31]
	ds_read_b64_tr_b16 v[222:223], v192 offset:0x3600
	ds_read_b64_tr_b16 v[224:225], v192 offset:0x3e00
	v_add_f32_e32 v174, v106, v174
	v_add_f32_e32 v174, v107, v174
	s_waitcnt vmcnt(0)
	s_barrier
	ds_read_b128 v[154:157], v194 offset:49152
	ds_read_b128 v[158:161], v194 offset:57344
	ds_read_b128 v[162:165], v197 offset:49152
	ds_read_b128 v[166:169], v197 offset:57344
	s_waitcnt lgkmcnt(10)
	v_mfma_f32_32x32x16_bf16 v[0:15], v[130:133], v[90:93], v[0:15]
	v_add_f32_e32 v174, v108, v174
	v_cvt_pk_bf16_f32 v130, v96, v97
	v_cvt_pk_bf16_f32 v131, v98, v99
	v_cvt_pk_bf16_f32 v132, v100, v101
	v_cvt_pk_bf16_f32 v133, v102, v103
	s_waitcnt lgkmcnt(8)
	v_mfma_f32_32x32x16_bf16 v[0:15], v[134:137], v[214:217], v[0:15]
	v_cvt_pk_bf16_f32 v134, v104, v105
	v_cvt_pk_bf16_f32 v135, v106, v107
	v_cvt_pk_bf16_f32 v136, v108, v176
	v_cvt_pk_bf16_f32 v137, v172, v80
	v_permlane32_swap_b32_e32 v130, v132
	v_permlane32_swap_b32_e32 v131, v133
	s_waitcnt lgkmcnt(6)
	v_mfma_f32_32x32x16_bf16 v[0:15], v[82:85], v[218:221], v[0:15]
	v_permlane32_swap_b32_e32 v134, v136
	v_permlane32_swap_b32_e32 v135, v137
	v_pk_add_f32 v[82:83], v[176:177], v[174:175]
	v_pk_add_f32 v[82:83], v[172:173], v[82:83]
	v_pk_add_f32 v[174:175], v[80:81], v[82:83]
	v_xor_b32_e32 v171, 0x10000, v171
	v_xor_b32_e32 v192, 0x10000, v192
	s_xor_b32 vcc_hi, vcc_hi, 0x10000
	s_waitcnt lgkmcnt(4)
	v_mfma_f32_32x32x16_bf16 v[0:15], v[86:89], v[222:225], v[0:15]
	s_add_i32 s9, s7, 2
	s_add_i32 s7, s7, -1
	v_mov_b32_e32 v173, v175
	s_cmp_ge_i32 s7, s6
	s_mov_b32 s7, s9
	s_cbranch_scc0 .Lattn_diff_top
	s_waitcnt lgkmcnt(0)
	s_branch .LBB0_609
